# stack8 + P2: three-tile workgroups take their tiles in reverse order (k tiles with the f32 cache stores first)
# speedup vs baseline: 1.0013x; 1.0013x over previous
.LBB0_157:
	v_writelane_b32 v255, s92, 13
	v_writelane_b32 v255, s86, 14
	s_cmp_lt_i32 s54, 3
	s_cselect_b64 s[40:41], -1, 0
	v_writelane_b32 v255, s87, 15
	v_writelane_b32 v255, s88, 16
	s_add_u32 s60, s18, 0x6000000
	s_addc_u32 s61, s19, 0
	v_writelane_b32 v255, s89, 17
	v_writelane_b32 v255, s94, 18
	s_add_u32 s52, s18, 0x9400000
	s_addc_u32 s53, s19, 0
	v_writelane_b32 v255, s95, 19
	v_writelane_b32 v255, s90, 20
	s_and_b64 s[0:1], s[40:41], s[6:7]
	s_andn2_b64 vcc, exec, s[0:1]
	v_writelane_b32 v255, s91, 21
	v_writelane_b32 v255, s54, 22
	v_writelane_b32 v255, s55, 23
	v_writelane_b32 v255, s96, 24
	s_nop 1
	v_writelane_b32 v255, s97, 25
	s_cbranch_vccnz .LBB0_465
	s_cmpk_lt_i32 s92, 0x280
	s_mov_b64 s[4:5], s[90:91]
	s_mov_b64 s[6:7], s[90:91]
	s_cselect_b64 s[42:43], -1, 0
	s_cmpk_gt_i32 s92, 0x27f
	v_readfirstlane_b32 s0, v0
	s_cbranch_scc1 .LBB0_160
	s_cmpk_lt_u32 s92, 0x80
	s_cselect_b32 s98, 0x200, 0
	s_add_i32 s98, s98, s92
	s_ashr_i32 s1, s98, 31
	s_lshr_b32 s1, s1, 29
	s_add_i32 s1, s98, s1
	s_ashr_i32 s2, s1, 3
	s_and_b32 s1, s1, -8
	s_sub_i32 s1, s98, s1
	s_cmp_lt_i32 s1, 0
	s_movk_i32 s3, 0x51
	s_cselect_b32 s3, s3, 0x50
	s_mul_i32 s1, s1, s3
	s_add_i32 s1, s1, s2
	s_mul_hi_i32 s2, s1, 0x66666667
	s_lshr_b32 s3, s2, 31
	s_ashr_i32 s2, s2, 6
	s_add_i32 s2, s2, s3
	s_lshl_b32 s3, s2, 3
	s_mulk_i32 s2, 0xa0
	s_sub_i32 s1, s1, s2
	s_sext_i32_i16 s2, s1
	s_bfe_u32 s2, s2, 0x3001c
	s_add_i32 s2, s1, s2
	s_sext_i32_i16 s8, s2
	s_and_b32 s2, s2, 0xfff8
	s_sub_i32 s1, s1, s2
	s_sext_i32_i16 s1, s1
	s_add_i32 s2, s3, s1
	s_ashr_i32 s20, s8, 3
	s_lshl_b32 s8, s2, 1
	s_ashr_i32 s9, s8, 31
	s_lshl_b64 s[8:9], s[8:9], 19
	s_add_u32 s10, s62, s8
	s_addc_u32 s11, s63, s9
	s_add_u32 s8, s10, 0x80000
	s_addc_u32 s9, s11, 0
	s_lshl_b32 s12, s20, 1
	s_ashr_i32 s13, s12, 31
	s_lshl_b64 s[12:13], s[12:13], 19
	s_add_u32 s84, s36, s12
	s_addc_u32 s85, s37, s13
	s_add_u32 s12, s84, 0x80000
	s_addc_u32 s13, s85, 0
	s_andn2_b64 vcc, exec, s[42:43]
	s_cbranch_vccz .LBB0_161
	s_branch .LBB0_431

.LBB0_166:
	v_readlane_b32 s6, v255, 20
	v_readlane_b32 s7, v255, 21
	s_load_dword s7, s[6:7], 0xe0
	s_add_i32 s48, s48, 1
	s_sub_i32 s98, 2, s48
	s_cmp_gt_u32 s48, 2
	s_cselect_b32 s98, s48, s98
	s_cmpk_lt_u32 s92, 0x80
	s_cselect_b32 s98, s98, s48
	s_mul_i32 s3, s98, s94
	s_waitcnt lgkmcnt(0)
	s_mul_hi_u32 s6, s98, s7
	s_add_i32 s6, s6, s3
	s_mul_i32 s3, s98, s7
	s_add_u32 s86, s3, s92
	s_addc_u32 s87, s6, s95
	v_cmp_gt_i64_e32 vcc, s[86:87], v[152:153]
	v_cmp_lt_i64_e64 s[6:7], s[86:87], v[150:151]
	s_cbranch_vccnz .LBB0_168
	s_ashr_i32 s3, s86, 31
	s_lshr_b32 s3, s3, 29
	s_add_i32 s3, s86, s3
	s_ashr_i32 s21, s3, 3
	s_and_b32 s3, s3, -8
	s_sub_i32 s3, s86, s3
	s_cmp_lt_i32 s3, 0
	s_movk_i32 s35, 0x51
	s_cselect_b32 s35, s35, 0x50
	s_mul_i32 s3, s3, s35
	s_add_i32 s3, s3, s21
	s_mul_hi_i32 s21, s3, 0x66666667
	s_lshr_b32 s35, s21, 31
	s_ashr_i32 s21, s21, 6
	s_add_i32 s21, s21, s35
	s_lshl_b32 s35, s21, 3
	s_sub_i32 s40, 32, s35
	s_min_i32 s40, s40, 8
	s_abs_i32 s49, s40
	v_cvt_f32_u32_e32 v2, s49
	s_sub_i32 s76, 0, s49
	s_mulk_i32 s21, 0xa0
	s_sub_i32 s3, s3, s21
	v_rcp_iflag_f32_e32 v2, v2
	s_abs_i32 s21, s3
	s_xor_b32 s50, s3, s40
	s_ashr_i32 s50, s50, 31
	v_mul_f32_e32 v2, 0x4f7ffffe, v2
	v_cvt_u32_f32_e32 v2, v2
	s_nop 0
	v_readfirstlane_b32 s77, v2
	s_mul_i32 s76, s76, s77
	s_mul_hi_u32 s76, s77, s76
	s_add_i32 s77, s77, s76
	s_mul_hi_u32 s76, s21, s77
	s_mul_i32 s77, s76, s49
	s_sub_i32 s21, s21, s77
	s_add_i32 s78, s76, 1
	s_sub_i32 s77, s21, s49
	s_cmp_ge_u32 s21, s49
	s_cselect_b32 s76, s78, s76
	s_cselect_b32 s21, s77, s21
	s_add_i32 s77, s76, 1
	s_cmp_ge_u32 s21, s49
	s_cselect_b32 s21, s77, s76
	s_xor_b32 s21, s21, s50
	s_sub_i32 s49, s21, s50
	s_mul_i32 s21, s49, s40
	s_sub_i32 s3, s3, s21
	s_add_i32 s35, s35, s3
	s_cmp_lg_u32 s48, 1
	s_cbranch_scc1 .Lp2_noswap
	s_cmp_lt_i32 s49, 10
	s_cselect_b32 s3, 10, -10
	s_add_i32 s49, s49, s3
